# 64-byte alignment of the four attention inner-loop heads (instruction-fetch alignment)
# baseline (speedup 1.0000x reference)
; #define LAS __attribute__((address_space(3)))
; #define WAIT_BAR0() asm volatile("s_waitcnt vmcnt(0) lgkmcnt(0)\n\ts_barrier" ::: "memory")
; template <int MODE, int HD>
; __device__ __forceinline__ unsigned attn_unit(const bf16_t* Qb, const bf16_t* Kb, const bf16_t* Vb, int pq, int pk, bf16_t* Ob, int q0, const float* logf, unsigned char* shm, unsigned* qctr) {
;     ...
;     for (int it = 0; it <= T0; ++it) {
;         const int t = T0 - it, sl = it & 3;
;         { const int ahead = T0 - it;
;           if (ahead >= 2) { if (NP == 1) asm volatile("s_waitcnt vmcnt(4) lgkmcnt(0)\n\ts_barrier" ::: "memory"); else asm volatile("s_waitcnt vmcnt(8) lgkmcnt(0)\n\ts_barrier" ::: "memory"); }
;           else if (ahead == 1) { if (NP == 1) asm volatile("s_waitcnt vmcnt(2) lgkmcnt(0)\n\ts_barrier" ::: "memory"); else asm volatile("s_waitcnt vmcnt(4) lgkmcnt(0)\n\ts_barrier" ::: "memory"); }
;           else WAIT_BAR0(); }
;         if ((MODE == 0 || MODE == 1) && it > 0) {
;             const u32x4 f0 = *(const LAS u32x4*)(FLG + ((it - 1) & 1) * 8), f1 = *(const LAS u32x4*)(FLG + ((it - 1) & 1) * 8 + 4);
;             if ((f0.x & f0.y & f0.z & f0.w & f1.x & f1.y & f1.z & f1.w) != 0u) break;
;         }
.LBB0_466:
	s_waitcnt vmcnt(0) lgkmcnt(0)
	s_barrier
	s_mov_b64 s[6:7], 0
	.p2align	6

; template <int MODE, int HD>
; __device__ __forceinline__ unsigned attn_unit(const bf16_t* Qb, const bf16_t* Kb, const bf16_t* Vb, int pq, int pk, bf16_t* Ob, int q0, const float* logf, unsigned char* shm, unsigned* qctr) {
;     ...
;     for (int it = 0; it <= T0; ++it) {
;         const int t = T0 - it, sl = it & 3;
.LBB0_497:
	s_or_b64 exec, exec, s[4:5]
	s_add_i32 s55, s55, 8
	s_addk_i32 s54, 0x2000
	s_add_i32 s24, s24, -1
	s_sub_i32 s34, s34, 64
	s_cmp_eq_u32 s24, -1
	s_cselect_b64 s[4:5], -1, 0
	s_and_b64 vcc, exec, s[4:5]
	s_cbranch_vccnz .LBB0_506
	.p2align	6

; #define XW(i, val) do { if ((i) < 16) p0[(i) & 15] = (val); else p1[(i) & 15] = (val); } while (0)
; template <int MODE, int HD>
; __device__ __forceinline__ unsigned attn_unit(const bf16_t* Qb, const bf16_t* Kb, const bf16_t* Vb, int pq, int pk, bf16_t* Ob, int q0, const float* logf, unsigned char* shm, unsigned* qctr) {
;     ...
;                 if (MODE == 1 && diag) {
; #pragma unroll
;                     for (int i = 0; i < 32; ++i) { if (kv0 + KVL(i) > qg) XW(i, -INFINITY); }
;     ...
;         if (MODE == 0) { const bool notdone = (t > tw) || __any(R >= SB_THR); wdone = !notdone; if (lane == 0) FLG[(it & 1) * 8 + wid] = notdone ? 0u : 1u; }
;         if (MODE == 1) {
;             bool notdone = true;
;             if (t <= tw && t >= 1 && !wdone) { const float bound = qn * CS[4096 + 64 + (t - 1)] + CS[64 * t - 1] - mrow;     notdone = __any(!(bound < -153.0f)); }
;             if (wdone) notdone = false; wdone = !notdone;
;             if (lane == 0) FLG[(it & 1) * 8 + wid] = notdone ? 0u : 1u; }
.LBB0_564:
	s_cmp_lg_u32 0, -1
	s_cselect_b32 s4, 0, 0
	s_lshl_b32 s5, s37, 2
	s_add_i32 s25, s4, s5
	s_add_i32 s25, s25, 0x20000
	s_and_saveexec_b64 s[4:5], s[40:41]
	v_cndmask_b32_e64 v34, 0, 1, s[20:21]
	v_mov_b32_e32 v35, s25
	ds_write_b32 v35, v34
	s_or_b64 exec, exec, s[4:5]
	s_andn2_b64 vcc, exec, s[0:1]
	s_cbranch_vccnz .LBB0_598
	s_cmp_lg_u32 0, -1
	s_cselect_b32 s0, 0, 0
	v_lshl_or_b32 v34, s3, 6, v121
	s_add_i32 s23, s48, s0
	v_cmp_gt_i32_e64 s[0:1], v34, v124
	v_or_b32_e32 v35, 2, v34
	s_lshl_b32 s12, s38, 2
	v_writelane_b32 v255, s0, 14
	v_cmp_lt_i32_e64 s[46:47], v34, v124
	s_add_i32 s44, s12, 0x140f4
	v_writelane_b32 v255, s1, 15
	v_cmp_gt_i32_e64 s[0:1], v35, v124
	v_or_b32_e32 v35, 3, v34
	s_lshl_b32 s12, s38, 8
	v_writelane_b32 v255, s0, 16
	s_add_i32 s24, s24, s2
	s_add_i32 s45, s12, 0xfdfc
	v_writelane_b32 v255, s1, 17
	v_cmp_gt_i32_e64 s[0:1], v35, v124
	v_or_b32_e32 v35, 8, v34
	v_cmp_gt_i32_e64 s[52:53], v35, v124
	v_or_b32_e32 v35, 9, v34
	v_cmp_gt_i32_e64 s[54:55], v35, v124
	v_or_b32_e32 v35, 10, v34
	v_cmp_gt_i32_e64 s[56:57], v35, v124
	v_or_b32_e32 v35, 11, v34
	v_cmp_gt_i32_e64 s[58:59], v35, v124
	v_or_b32_e32 v35, 16, v34
	v_cmp_gt_i32_e64 s[60:61], v35, v124
	v_or_b32_e32 v35, 17, v34
	v_cmp_gt_i32_e64 s[62:63], v35, v124
	v_or_b32_e32 v35, 18, v34
	v_cmp_gt_i32_e64 s[64:65], v35, v124
	v_or_b32_e32 v35, 19, v34
	v_cmp_gt_i32_e64 s[66:67], v35, v124
	v_or_b32_e32 v35, 24, v34
	v_cmp_gt_i32_e64 s[68:69], v35, v124
	v_or_b32_e32 v35, 25, v34
	v_cmp_gt_i32_e64 s[70:71], v35, v124
	v_or_b32_e32 v35, 26, v34
	v_cmp_gt_i32_e64 s[72:73], v35, v124
	v_or_b32_e32 v35, 27, v34
	v_cmp_gt_i32_e64 s[74:75], v35, v124
	v_or_b32_e32 v35, 32, v34
	v_cmp_gt_i32_e64 s[76:77], v35, v124
	v_or_b32_e32 v35, 33, v34
	v_cmp_gt_i32_e64 s[78:79], v35, v124
	v_or_b32_e32 v35, 34, v34
	v_cmp_gt_i32_e64 s[80:81], v35, v124
	v_or_b32_e32 v35, 35, v34
	v_cmp_gt_i32_e64 s[82:83], v35, v124
	v_or_b32_e32 v35, 40, v34
	v_cmp_gt_i32_e64 s[84:85], v35, v124
	v_or_b32_e32 v35, 41, v34
	v_cmp_gt_i32_e64 s[86:87], v35, v124
	v_or_b32_e32 v35, 42, v34
	v_cmp_gt_i32_e64 s[88:89], v35, v124
	v_or_b32_e32 v35, 43, v34
	v_cmp_gt_i32_e64 s[90:91], v35, v124
	v_or_b32_e32 v35, 48, v34
	v_cmp_gt_i32_e64 s[92:93], v35, v124
	v_or_b32_e32 v35, 49, v34
	v_cmp_gt_i32_e64 s[94:95], v35, v124
	v_or_b32_e32 v35, 50, v34
	v_writelane_b32 v255, s0, 18
	v_cmp_gt_i32_e64 s[96:97], v35, v124
	v_or_b32_e32 v35, 51, v34
	v_writelane_b32 v255, s1, 19
	v_cmp_gt_i32_e64 s[0:1], v35, v124
	v_or_b32_e32 v35, 56, v34
	v_cmp_gt_i32_e64 s[4:5], v35, v124
	v_or_b32_e32 v35, 57, v34
	v_cmp_gt_i32_e64 s[6:7], v35, v124
	v_or_b32_e32 v35, 58, v34
	v_or_b32_e32 v34, 59, v34
	v_cmp_gt_i32_e64 s[10:11], v34, v124
	s_add_i32 s12, s12, 0xfe00
	s_sub_i32 s48, s38, s3
	v_add_u32_e32 v34, s24, v126
	s_addk_i32 s2, 0xfec0
	s_mov_b32 s22, 0
	s_mov_b32 s30, 0x8000
	s_add_i32 s35, s23, 0x8000
	v_lshl_add_u32 v128, v121, 2, s39
	s_mov_b32 s31, 8
	v_cmp_gt_i32_e64 s[8:9], v35, v124
	v_lshl_or_b32 v124, v118, 4, s12
	s_add_i32 s48, s48, -2
	v_add_u32_e32 v126, 0xfffffec0, v34
	v_add_u32_e32 v130, s2, v116
	.p2align	6

; #define LAS __attribute__((address_space(3)))
; template <int MODE, int HD>
; __device__ __forceinline__ unsigned attn_unit(const bf16_t* Qb, const bf16_t* Kb, const bf16_t* Vb, int pq, int pk, bf16_t* Ob, int q0, const float* logf, unsigned char* shm, unsigned* qctr) {
;     ...
;         if ((MODE == 0 || MODE == 1) && it > 0) {
;             const u32x4 f0 = *(const LAS u32x4*)(FLG + ((it - 1) & 1) * 8), f1 = *(const LAS u32x4*)(FLG + ((it - 1) & 1) * 8 + 4);
;             if ((f0.x & f0.y & f0.z & f0.w & f1.x & f1.y & f1.z & f1.w) != 0u) break;
;         }
;         if (t >= 3) DMA_TILE(t - 3, (it + 3) & 3);
;         if (t <= tw && !wdone) {
.LBB0_609:
	s_and_b64 vcc, exec, s[6:7]
	s_cbranch_vccnz .LBB0_617
	.p2align	6
